# attention epilogue output stores staged through wave-private LDS and written as full 128-byte row segments (8 rows x 128 B per instruction) instead of 32 rows x 32 B gather-like stores
# baseline (speedup 1.0000x reference)
; DI unsigned pk2(float lo, float hi) { f32x2 v = {lo, hi}; return __builtin_bit_cast(unsigned, __builtin_convertvector(v, bf2_t)); }
; DI float bflo(unsigned w) { return __uint_as_float(w << 16); }
; DI float bfhi(unsigned w) { return __uint_as_float(w & 0xffff0000u); }
; DI void attn_unit(const Params& p, int b, int h, int qb, LAS unsigned char* lds, int tid, int lane, int wave) {
;     ...
;     if (g == 0) {
;         const float m1 = MB[64 * 64], l1 = MB[65 * 64];
;         const float m = fmaxf(mrow, m1);
;         const float a0 = __builtin_amdgcn_exp2f(mrow - m), a1 = __builtin_amdgcn_exp2f(m1 - m);
;         const float inv = 1.0f / (lrow * a0 + l1 * a1);
;         const size_t tok = tokb + qr0 + r;
;         const bf16_t* gp = Z + tok * ZLD + Z_MG + h * 128 + 4 * hh;
;         bf16_t* op = OB + tok * DM + 512 + h * 128 + 4 * hh;
;         u32x2 gw[4][4];
; #pragma unroll
;         for (int i = 0; i < 4; ++i)
; #pragma unroll
;             for (int q = 0; q < 4; ++q) gw[i][q] = *(const u32x2*)(gp + i * 32 + q * 8);
; #pragma unroll
;         for (int i = 0; i < 4; ++i)
; #pragma unroll
;             for (int q = 0; q < 4; ++q) {
;                 float gv[4] = {bflo(gw[i][q].x), bfhi(gw[i][q].x), bflo(gw[i][q].y), bfhi(gw[i][q].y)}; float ov[4];
; #pragma unroll
;                 for (int e = 0; e < 4; ++e) { const float val = (o[i][q * 4 + e] * a0 + MB[(i * 16 + q * 4 + e) * 64] * a1) * inv; ov[e] = val * (gv[e] / (1.f + __expf(-gv[e]))); }
;                 *(u32x2*)(op + i * 32 + q * 8) = (u32x2){pk2(ov[0], ov[1]), pk2(ov[2], ov[3])};
;             }
.Le1_wd:
	s_xor_b32 s0, s21, 1
	s_mulk_i32 s0, 0x2200
	v_add_u32_e32 v150, s0, v104
	s_waitcnt lgkmcnt(0)
	s_barrier
	ds_read2st64_b32 v[70:71], v150 offset0:32 offset1:33
	ds_read2st64_b32 v[110:111], v150 offset0:0 offset1:1
	ds_read2st64_b32 v[112:113], v150 offset0:2 offset1:3
	ds_read2st64_b32 v[114:115], v150 offset0:4 offset1:5
	ds_read2st64_b32 v[116:117], v150 offset0:6 offset1:7
	ds_read2st64_b32 v[118:119], v150 offset0:8 offset1:9
	ds_read2st64_b32 v[120:121], v150 offset0:10 offset1:11
	ds_read2st64_b32 v[122:123], v150 offset0:12 offset1:13
	ds_read2st64_b32 v[124:125], v150 offset0:14 offset1:15
	ds_read2st64_b32 v[126:127], v150 offset0:16 offset1:17
	ds_read2st64_b32 v[128:129], v150 offset0:18 offset1:19
	ds_read2st64_b32 v[130:131], v150 offset0:20 offset1:21
	ds_read2st64_b32 v[132:133], v150 offset0:22 offset1:23
	ds_read2st64_b32 v[134:135], v150 offset0:24 offset1:25
	ds_read2st64_b32 v[136:137], v150 offset0:26 offset1:27
	ds_read2st64_b32 v[138:139], v150 offset0:28 offset1:29
	ds_read2st64_b32 v[140:141], v150 offset0:30 offset1:31
	v_max_f32_e32 v0, v204, v204
	s_lshl_b32 s0, s2, 8
	s_mov_b32 s1, s93
	v_ashrrev_i32_e32 v183, 31, v182
	s_waitcnt lgkmcnt(0)
	v_max_f32_e32 v66, v70, v70
	v_max_f32_e32 v0, v0, v66
	v_sub_f32_e32 v66, v204, v0
	v_sub_f32_e32 v0, v70, v0
	v_exp_f32_e32 v66, v66
	v_exp_f32_e32 v67, v0
	v_mov_b32_e32 v69, v71
	v_lshlrev_b32_e32 v0, 12, v202
	v_lshlrev_b64 v[102:103], 1, v[182:183]
	v_pk_mul_f32 v[68:69], v[68:69], v[66:67]
	s_mov_b64 s[4:5], 0x4600c00
	v_add_f32_e32 v105, v68, v69
	v_lshl_add_u64 v[68:69], s[50:51], 0, v[0:1]
	v_lshl_add_u64 v[70:71], v[68:69], 0, s[0:1]
	v_lshlrev_b32_e32 v0, 11, v202
	v_lshl_add_u64 v[70:71], v[70:71], 0, v[102:103]
	v_sub_co_u32_e32 v72, vcc, 0, v0
	v_lshl_add_u64 v[106:107], v[70:71], 0, s[4:5]
	s_nop 0
	v_subb_co_u32_e64 v73, s[4:5], 0, 0, vcc
	v_lshl_add_u64 v[68:69], v[68:69], 0, v[72:73]
	v_lshl_add_u64 v[68:69], v[68:69], 0, s[0:1]
	s_mov_b32 s0, 0x4600000
	v_add_co_u32_e32 v70, vcc, s0, v70
	v_div_scale_f32 v0, s[0:1], v105, v105, 1.0
	s_nop 0
	v_addc_co_u32_e32 v71, vcc, 0, v71, vcc
	s_lshl_b32 vcc_lo, s21, 7
	v_lshl_add_u32 v152, v182, 1, vcc_lo
	v_rcp_f32_e32 v106, v0
	v_lshl_add_u64 v[102:103], v[68:69], 0, v[102:103]
	s_mov_b64 s[0:1], 0xae00400
	v_lshl_add_u64 v[68:69], v[102:103], 0, s[0:1]
	v_fma_f32 v107, -v0, v106, 1.0
	v_fmac_f32_e32 v106, v107, v106
	v_div_scale_f32 v107, vcc, 1.0, v105, 1.0
	v_mul_f32_e32 v108, v107, v106
	v_fma_f32 v109, -v0, v108, v107
	v_fmac_f32_e32 v108, v109, v106
	v_fma_f32 v0, -v0, v108, v107
	v_div_fmas_f32 v0, v0, v106, v108
	v_div_fixup_f32 v0, v0, v105, 1.0
	v_mov_b32_e32 v72, v67
	v_mov_b32_e32 v153, 0
	v_lshl_add_u64 v[148:149], v[152:153], 0, v[68:69]
	s_waitcnt vmcnt(6)
	v_pk_mul_f32 v[154:155], v[72:73], v[110:111] op_sel_hi:[0,1]
	v_pk_mul_f32 v[156:157], v[72:73], v[112:113] op_sel_hi:[0,1]
	v_pk_mul_f32 v[158:159], v[72:73], v[114:115] op_sel_hi:[0,1]
	v_pk_mul_f32 v[160:161], v[72:73], v[116:117] op_sel_hi:[0,1]
	v_lshlrev_b32_e32 v162, 16, v230
	v_and_b32_e32 v163, 0xffff0000, v230
	v_lshlrev_b32_e32 v164, 16, v231
	v_and_b32_e32 v165, 0xffff0000, v231
	v_lshlrev_b32_e32 v166, 16, v232
	v_and_b32_e32 v167, 0xffff0000, v232
	v_lshlrev_b32_e32 v168, 16, v233
	v_and_b32_e32 v169, 0xffff0000, v233
	v_pk_fma_f32 v[154:155], v[50:51], v[66:67], v[154:155] op_sel_hi:[1,0,1]
	v_pk_fma_f32 v[156:157], v[52:53], v[66:67], v[156:157] op_sel_hi:[1,0,1]
	v_pk_fma_f32 v[158:159], v[54:55], v[66:67], v[158:159] op_sel_hi:[1,0,1]
	v_pk_fma_f32 v[160:161], v[56:57], v[66:67], v[160:161] op_sel_hi:[1,0,1]
	v_mul_f32_e32 v170, 0xbfb8aa3b, v162
	v_mul_f32_e32 v171, 0xbfb8aa3b, v163
	v_mul_f32_e32 v172, 0xbfb8aa3b, v164
	v_mul_f32_e32 v173, 0xbfb8aa3b, v165
	v_mul_f32_e32 v174, 0xbfb8aa3b, v166
	v_mul_f32_e32 v175, 0xbfb8aa3b, v167
	v_mul_f32_e32 v176, 0xbfb8aa3b, v168
	v_mul_f32_e32 v177, 0xbfb8aa3b, v169
	v_pk_mul_f32 v[154:155], v[0:1], v[154:155] op_sel_hi:[0,1]
	v_pk_mul_f32 v[156:157], v[0:1], v[156:157] op_sel_hi:[0,1]
	v_pk_mul_f32 v[158:159], v[0:1], v[158:159] op_sel_hi:[0,1]
	v_pk_mul_f32 v[160:161], v[0:1], v[160:161] op_sel_hi:[0,1]
	v_exp_f32_e32 v170, v170
	v_exp_f32_e32 v171, v171
	v_exp_f32_e32 v172, v172
	v_exp_f32_e32 v173, v173
	v_exp_f32_e32 v174, v174
	v_exp_f32_e32 v175, v175
	v_exp_f32_e32 v176, v176
	v_exp_f32_e32 v177, v177
	v_pk_add_f32 v[170:171], v[170:171], 1.0 op_sel_hi:[1,0]
	v_pk_add_f32 v[172:173], v[172:173], 1.0 op_sel_hi:[1,0]
	v_pk_add_f32 v[174:175], v[174:175], 1.0 op_sel_hi:[1,0]
	v_pk_add_f32 v[176:177], v[176:177], 1.0 op_sel_hi:[1,0]
	v_rcp_f32_e32 v170, v170
	v_rcp_f32_e32 v171, v171
	v_rcp_f32_e32 v172, v172
	v_rcp_f32_e32 v173, v173
	v_rcp_f32_e32 v174, v174
	v_rcp_f32_e32 v175, v175
	v_rcp_f32_e32 v176, v176
	v_rcp_f32_e32 v177, v177
	v_pk_mul_f32 v[162:163], v[162:163], v[170:171]
	v_pk_mul_f32 v[164:165], v[164:165], v[172:173]
	v_pk_mul_f32 v[166:167], v[166:167], v[174:175]
	v_pk_mul_f32 v[168:169], v[168:169], v[176:177]
	v_pk_mul_f32 v[154:155], v[162:163], v[154:155]
	v_pk_mul_f32 v[156:157], v[164:165], v[156:157]
	v_pk_mul_f32 v[158:159], v[166:167], v[158:159]
	v_pk_mul_f32 v[160:161], v[168:169], v[160:161]
	v_cvt_pk_bf16_f32 v90, v154, v155
	v_cvt_pk_bf16_f32 v91, v156, v157
	v_cvt_pk_bf16_f32 v92, v158, v159
	v_cvt_pk_bf16_f32 v93, v160, v161
	v_mbcnt_lo_u32_b32 v178, -1, 0
	v_mbcnt_hi_u32_b32 v178, -1, v178
	s_mul_i32 s4, s33, 0x1200
	s_add_u32 s4, s4, 0x11000
	v_and_b32_e32 v179, 31, v178
	v_lshrrev_b32_e32 v180, 5, v178
	v_mul_u32_u24_e32 v179, 0x90, v179
	v_lshl_add_u32 v179, v180, 3, v179
	v_add_u32_e32 v179, s4, v179
	v_readfirstlane_b32 s0, v148
	v_readfirstlane_b32 s1, v149
	ds_write_b64 v179, v[90:91] offset:0
	ds_write_b64 v179, v[92:93] offset:16
	s_waitcnt vmcnt(4)
; DI unsigned pk2(float lo, float hi) { f32x2 v = {lo, hi}; return __builtin_bit_cast(unsigned, __builtin_convertvector(v, bf2_t)); }
; DI float bflo(unsigned w) { return __uint_as_float(w << 16); }
; DI float bfhi(unsigned w) { return __uint_as_float(w & 0xffff0000u); }
; DI void attn_unit(const Params& p, int b, int h, int qb, LAS unsigned char* lds, int tid, int lane, int wave) {
;     ...
; #pragma unroll
;         for (int i = 0; i < 4; ++i)
; #pragma unroll
;             for (int q = 0; q < 4; ++q) gw[i][q] = *(const u32x2*)(gp + i * 32 + q * 8);
; #pragma unroll
;         for (int i = 0; i < 4; ++i)
; #pragma unroll
;             for (int q = 0; q < 4; ++q) {
;                 float gv[4] = {bflo(gw[i][q].x), bfhi(gw[i][q].x), bflo(gw[i][q].y), bfhi(gw[i][q].y)}; float ov[4];
; #pragma unroll
;                 for (int e = 0; e < 4; ++e) { const float val = (o[i][q * 4 + e] * a0 + MB[(i * 16 + q * 4 + e) * 64] * a1) * inv; ov[e] = val * (gv[e] / (1.f + __expf(-gv[e]))); }
;                 *(u32x2*)(op + i * 32 + q * 8) = (u32x2){pk2(ov[0], ov[1]), pk2(ov[2], ov[3])};
;             }
	v_pk_mul_f32 v[154:155], v[72:73], v[118:119] op_sel_hi:[0,1]
	v_pk_mul_f32 v[156:157], v[72:73], v[120:121] op_sel_hi:[0,1]
	v_pk_mul_f32 v[158:159], v[72:73], v[122:123] op_sel_hi:[0,1]
	v_pk_mul_f32 v[160:161], v[72:73], v[124:125] op_sel_hi:[0,1]
	v_lshlrev_b32_e32 v162, 16, v234
	v_and_b32_e32 v163, 0xffff0000, v234
	v_lshlrev_b32_e32 v164, 16, v235
	v_and_b32_e32 v165, 0xffff0000, v235
	v_lshlrev_b32_e32 v166, 16, v236
	v_and_b32_e32 v167, 0xffff0000, v236
	v_lshlrev_b32_e32 v168, 16, v237
	v_and_b32_e32 v169, 0xffff0000, v237
	v_pk_fma_f32 v[154:155], v[58:59], v[66:67], v[154:155] op_sel_hi:[1,0,1]
	v_pk_fma_f32 v[156:157], v[60:61], v[66:67], v[156:157] op_sel_hi:[1,0,1]
	v_pk_fma_f32 v[158:159], v[62:63], v[66:67], v[158:159] op_sel_hi:[1,0,1]
	v_pk_fma_f32 v[160:161], v[64:65], v[66:67], v[160:161] op_sel_hi:[1,0,1]
	v_mul_f32_e32 v170, 0xbfb8aa3b, v162
	v_mul_f32_e32 v171, 0xbfb8aa3b, v163
	v_mul_f32_e32 v172, 0xbfb8aa3b, v164
	v_mul_f32_e32 v173, 0xbfb8aa3b, v165
	v_mul_f32_e32 v174, 0xbfb8aa3b, v166
	v_mul_f32_e32 v175, 0xbfb8aa3b, v167
	v_mul_f32_e32 v176, 0xbfb8aa3b, v168
	v_mul_f32_e32 v177, 0xbfb8aa3b, v169
	v_pk_mul_f32 v[154:155], v[0:1], v[154:155] op_sel_hi:[0,1]
	v_pk_mul_f32 v[156:157], v[0:1], v[156:157] op_sel_hi:[0,1]
	v_pk_mul_f32 v[158:159], v[0:1], v[158:159] op_sel_hi:[0,1]
	v_pk_mul_f32 v[160:161], v[0:1], v[160:161] op_sel_hi:[0,1]
	v_exp_f32_e32 v170, v170
	v_exp_f32_e32 v171, v171
	v_exp_f32_e32 v172, v172
	v_exp_f32_e32 v173, v173
	v_exp_f32_e32 v174, v174
	v_exp_f32_e32 v175, v175
	v_exp_f32_e32 v176, v176
	v_exp_f32_e32 v177, v177
	v_pk_add_f32 v[170:171], v[170:171], 1.0 op_sel_hi:[1,0]
	v_pk_add_f32 v[172:173], v[172:173], 1.0 op_sel_hi:[1,0]
	v_pk_add_f32 v[174:175], v[174:175], 1.0 op_sel_hi:[1,0]
	v_pk_add_f32 v[176:177], v[176:177], 1.0 op_sel_hi:[1,0]
	v_rcp_f32_e32 v170, v170
	v_rcp_f32_e32 v171, v171
	v_rcp_f32_e32 v172, v172
	v_rcp_f32_e32 v173, v173
	v_rcp_f32_e32 v174, v174
	v_rcp_f32_e32 v175, v175
	v_rcp_f32_e32 v176, v176
	v_rcp_f32_e32 v177, v177
	v_pk_mul_f32 v[162:163], v[162:163], v[170:171]
	v_pk_mul_f32 v[164:165], v[164:165], v[172:173]
	v_pk_mul_f32 v[166:167], v[166:167], v[174:175]
	v_pk_mul_f32 v[168:169], v[168:169], v[176:177]
	v_pk_mul_f32 v[154:155], v[162:163], v[154:155]
	v_pk_mul_f32 v[156:157], v[164:165], v[156:157]
	v_pk_mul_f32 v[158:159], v[166:167], v[158:159]
	v_pk_mul_f32 v[160:161], v[168:169], v[160:161]
	v_cvt_pk_bf16_f32 v94, v154, v155
	v_cvt_pk_bf16_f32 v95, v156, v157
	v_cvt_pk_bf16_f32 v96, v158, v159
	v_cvt_pk_bf16_f32 v97, v160, v161
	ds_write_b64 v179, v[94:95] offset:32
	ds_write_b64 v179, v[96:97] offset:48
	s_waitcnt vmcnt(2)
	v_pk_mul_f32 v[154:155], v[72:73], v[126:127] op_sel_hi:[0,1]
	v_pk_mul_f32 v[156:157], v[72:73], v[128:129] op_sel_hi:[0,1]
	v_pk_mul_f32 v[158:159], v[72:73], v[130:131] op_sel_hi:[0,1]
	v_pk_mul_f32 v[160:161], v[72:73], v[132:133] op_sel_hi:[0,1]
	v_lshlrev_b32_e32 v162, 16, v238
	v_and_b32_e32 v163, 0xffff0000, v238
	v_lshlrev_b32_e32 v164, 16, v239
	v_and_b32_e32 v165, 0xffff0000, v239
	v_lshlrev_b32_e32 v166, 16, v240
	v_and_b32_e32 v167, 0xffff0000, v240
	v_lshlrev_b32_e32 v168, 16, v241
	v_and_b32_e32 v169, 0xffff0000, v241
	v_pk_fma_f32 v[154:155], v[34:35], v[66:67], v[154:155] op_sel_hi:[1,0,1]
	v_pk_fma_f32 v[156:157], v[36:37], v[66:67], v[156:157] op_sel_hi:[1,0,1]
	v_pk_fma_f32 v[158:159], v[38:39], v[66:67], v[158:159] op_sel_hi:[1,0,1]
	v_pk_fma_f32 v[160:161], v[40:41], v[66:67], v[160:161] op_sel_hi:[1,0,1]
	v_mul_f32_e32 v170, 0xbfb8aa3b, v162
	v_mul_f32_e32 v171, 0xbfb8aa3b, v163
	v_mul_f32_e32 v172, 0xbfb8aa3b, v164
	v_mul_f32_e32 v173, 0xbfb8aa3b, v165
	v_mul_f32_e32 v174, 0xbfb8aa3b, v166
	v_mul_f32_e32 v175, 0xbfb8aa3b, v167
	v_mul_f32_e32 v176, 0xbfb8aa3b, v168
	v_mul_f32_e32 v177, 0xbfb8aa3b, v169
	v_pk_mul_f32 v[154:155], v[0:1], v[154:155] op_sel_hi:[0,1]
	v_pk_mul_f32 v[156:157], v[0:1], v[156:157] op_sel_hi:[0,1]
	v_pk_mul_f32 v[158:159], v[0:1], v[158:159] op_sel_hi:[0,1]
	v_pk_mul_f32 v[160:161], v[0:1], v[160:161] op_sel_hi:[0,1]
	v_exp_f32_e32 v170, v170
	v_exp_f32_e32 v171, v171
	v_exp_f32_e32 v172, v172
	v_exp_f32_e32 v173, v173
	v_exp_f32_e32 v174, v174
	v_exp_f32_e32 v175, v175
	v_exp_f32_e32 v176, v176
	v_exp_f32_e32 v177, v177
	v_pk_add_f32 v[170:171], v[170:171], 1.0 op_sel_hi:[1,0]
	v_pk_add_f32 v[172:173], v[172:173], 1.0 op_sel_hi:[1,0]
	v_pk_add_f32 v[174:175], v[174:175], 1.0 op_sel_hi:[1,0]
	v_pk_add_f32 v[176:177], v[176:177], 1.0 op_sel_hi:[1,0]
	v_rcp_f32_e32 v170, v170
	v_rcp_f32_e32 v171, v171
	v_rcp_f32_e32 v172, v172
	v_rcp_f32_e32 v173, v173
	v_rcp_f32_e32 v174, v174
	v_rcp_f32_e32 v175, v175
	v_rcp_f32_e32 v176, v176
	v_rcp_f32_e32 v177, v177
	v_pk_mul_f32 v[162:163], v[162:163], v[170:171]
	v_pk_mul_f32 v[164:165], v[164:165], v[172:173]
	v_pk_mul_f32 v[166:167], v[166:167], v[174:175]
	v_pk_mul_f32 v[168:169], v[168:169], v[176:177]
	v_pk_mul_f32 v[154:155], v[162:163], v[154:155]
	v_pk_mul_f32 v[156:157], v[164:165], v[156:157]
	v_pk_mul_f32 v[158:159], v[166:167], v[158:159]
	v_pk_mul_f32 v[160:161], v[168:169], v[160:161]
	v_cvt_pk_bf16_f32 v98, v154, v155
	v_cvt_pk_bf16_f32 v99, v156, v157
	v_cvt_pk_bf16_f32 v100, v158, v159
	v_cvt_pk_bf16_f32 v101, v160, v161
	ds_write_b64 v179, v[98:99] offset:64
	ds_write_b64 v179, v[100:101] offset:80
	s_waitcnt vmcnt(0)
; DI unsigned pk2(float lo, float hi) { f32x2 v = {lo, hi}; return __builtin_bit_cast(unsigned, __builtin_convertvector(v, bf2_t)); }
; DI float bflo(unsigned w) { return __uint_as_float(w << 16); }
; DI float bfhi(unsigned w) { return __uint_as_float(w & 0xffff0000u); }
; DI void attn_unit(const Params& p, int b, int h, int qb, LAS unsigned char* lds, int tid, int lane, int wave) {
;     ...
; #pragma unroll
;         for (int i = 0; i < 4; ++i)
; #pragma unroll
;             for (int q = 0; q < 4; ++q) gw[i][q] = *(const u32x2*)(gp + i * 32 + q * 8);
; #pragma unroll
;         for (int i = 0; i < 4; ++i)
; #pragma unroll
;             for (int q = 0; q < 4; ++q) {
;                 float gv[4] = {bflo(gw[i][q].x), bfhi(gw[i][q].x), bflo(gw[i][q].y), bfhi(gw[i][q].y)}; float ov[4];
; #pragma unroll
;                 for (int e = 0; e < 4; ++e) { const float val = (o[i][q * 4 + e] * a0 + MB[(i * 16 + q * 4 + e) * 64] * a1) * inv; ov[e] = val * (gv[e] / (1.f + __expf(-gv[e]))); }
;                 *(u32x2*)(op + i * 32 + q * 8) = (u32x2){pk2(ov[0], ov[1]), pk2(ov[2], ov[3])};
;             }
	v_pk_mul_f32 v[154:155], v[72:73], v[134:135] op_sel_hi:[0,1]
	v_pk_mul_f32 v[156:157], v[72:73], v[136:137] op_sel_hi:[0,1]
	v_pk_mul_f32 v[158:159], v[72:73], v[138:139] op_sel_hi:[0,1]
	v_pk_mul_f32 v[160:161], v[72:73], v[140:141] op_sel_hi:[0,1]
	v_lshlrev_b32_e32 v162, 16, v242
	v_and_b32_e32 v163, 0xffff0000, v242
	v_lshlrev_b32_e32 v164, 16, v243
	v_and_b32_e32 v165, 0xffff0000, v243
	v_lshlrev_b32_e32 v166, 16, v244
	v_and_b32_e32 v167, 0xffff0000, v244
	v_lshlrev_b32_e32 v168, 16, v245
	v_and_b32_e32 v169, 0xffff0000, v245
	v_pk_fma_f32 v[154:155], v[42:43], v[66:67], v[154:155] op_sel_hi:[1,0,1]
	v_pk_fma_f32 v[156:157], v[44:45], v[66:67], v[156:157] op_sel_hi:[1,0,1]
	v_pk_fma_f32 v[158:159], v[46:47], v[66:67], v[158:159] op_sel_hi:[1,0,1]
	v_pk_fma_f32 v[160:161], v[48:49], v[66:67], v[160:161] op_sel_hi:[1,0,1]
	v_mul_f32_e32 v170, 0xbfb8aa3b, v162
	v_mul_f32_e32 v171, 0xbfb8aa3b, v163
	v_mul_f32_e32 v172, 0xbfb8aa3b, v164
	v_mul_f32_e32 v173, 0xbfb8aa3b, v165
	v_mul_f32_e32 v174, 0xbfb8aa3b, v166
	v_mul_f32_e32 v175, 0xbfb8aa3b, v167
	v_mul_f32_e32 v176, 0xbfb8aa3b, v168
	v_mul_f32_e32 v177, 0xbfb8aa3b, v169
	v_pk_mul_f32 v[154:155], v[0:1], v[154:155] op_sel_hi:[0,1]
	v_pk_mul_f32 v[156:157], v[0:1], v[156:157] op_sel_hi:[0,1]
	v_pk_mul_f32 v[158:159], v[0:1], v[158:159] op_sel_hi:[0,1]
	v_pk_mul_f32 v[160:161], v[0:1], v[160:161] op_sel_hi:[0,1]
	v_exp_f32_e32 v170, v170
	v_exp_f32_e32 v171, v171
	v_exp_f32_e32 v172, v172
	v_exp_f32_e32 v173, v173
	v_exp_f32_e32 v174, v174
	v_exp_f32_e32 v175, v175
	v_exp_f32_e32 v176, v176
	v_exp_f32_e32 v177, v177
	v_pk_add_f32 v[170:171], v[170:171], 1.0 op_sel_hi:[1,0]
	v_pk_add_f32 v[172:173], v[172:173], 1.0 op_sel_hi:[1,0]
	v_pk_add_f32 v[174:175], v[174:175], 1.0 op_sel_hi:[1,0]
	v_pk_add_f32 v[176:177], v[176:177], 1.0 op_sel_hi:[1,0]
	v_rcp_f32_e32 v170, v170
	v_rcp_f32_e32 v171, v171
	v_rcp_f32_e32 v172, v172
	v_rcp_f32_e32 v173, v173
	v_rcp_f32_e32 v174, v174
	v_rcp_f32_e32 v175, v175
	v_rcp_f32_e32 v176, v176
	v_rcp_f32_e32 v177, v177
	v_pk_mul_f32 v[162:163], v[162:163], v[170:171]
	v_pk_mul_f32 v[164:165], v[164:165], v[172:173]
	v_pk_mul_f32 v[166:167], v[166:167], v[174:175]
	v_pk_mul_f32 v[168:169], v[168:169], v[176:177]
	v_pk_mul_f32 v[154:155], v[162:163], v[154:155]
	v_pk_mul_f32 v[156:157], v[164:165], v[156:157]
	v_pk_mul_f32 v[158:159], v[166:167], v[158:159]
	v_pk_mul_f32 v[160:161], v[168:169], v[160:161]
	v_cvt_pk_bf16_f32 v102, v154, v155
	v_cvt_pk_bf16_f32 v103, v156, v157
	v_cvt_pk_bf16_f32 v104, v158, v159
	v_cvt_pk_bf16_f32 v105, v160, v161
	ds_write_b64 v179, v[102:103] offset:96
	ds_write_b64 v179, v[104:105] offset:112
	v_lshrrev_b32_e32 v180, 3, v178
	v_and_b32_e32 v181, 7, v178
	v_mul_u32_u24_e32 v177, 0x90, v180
	v_lshl_add_u32 v177, v181, 4, v177
	v_add_u32_e32 v177, s4, v177
	v_lshlrev_b32_e32 v180, 11, v180
	v_lshl_add_u32 v180, v181, 4, v180
	s_waitcnt lgkmcnt(0)
	ds_read_b128 v[154:157], v177
	ds_read_b128 v[158:161], v177 offset:1152
	ds_read_b128 v[162:165], v177 offset:2304
	ds_read_b128 v[166:169], v177 offset:3456
	s_waitcnt lgkmcnt(3)
	global_store_dwordx4 v180, v[154:157], s[0:1]
	s_add_u32 s0, s0, 0x4000
	s_addc_u32 s1, s1, 0
	s_waitcnt lgkmcnt(2)
	global_store_dwordx4 v180, v[158:161], s[0:1]
	s_add_u32 s0, s0, 0x4000
	s_addc_u32 s1, s1, 0
	s_waitcnt lgkmcnt(1)
	global_store_dwordx4 v180, v[162:165], s[0:1]
	s_add_u32 s0, s0, 0x4000
	s_addc_u32 s1, s1, 0
	s_waitcnt lgkmcnt(0)
	global_store_dwordx4 v180, v[166:169], s[0:1]

; DI unsigned pk2(float lo, float hi) { f32x2 v = {lo, hi}; return __builtin_bit_cast(unsigned, __builtin_convertvector(v, bf2_t)); }
; DI float bflo(unsigned w) { return __uint_as_float(w << 16); }
; DI float bfhi(unsigned w) { return __uint_as_float(w & 0xffff0000u); }
; DI void attn_unit(const Params& p, int b, int h, int qb, LAS unsigned char* lds, int tid, int lane, int wave) {
;     ...
;     if (g == 0) {
;         const float m1 = MB[64 * 64], l1 = MB[65 * 64];
;         const float m = fmaxf(mrow, m1);
;         const float a0 = __builtin_amdgcn_exp2f(mrow - m), a1 = __builtin_amdgcn_exp2f(m1 - m);
;         const float inv = 1.0f / (lrow * a0 + l1 * a1);
;         const size_t tok = tokb + qr0 + r;
;         const bf16_t* gp = Z + tok * ZLD + Z_MG + h * 128 + 4 * hh;
;         bf16_t* op = OB + tok * DM + 512 + h * 128 + 4 * hh;
;         u32x2 gw[4][4];
; #pragma unroll
;         for (int i = 0; i < 4; ++i)
; #pragma unroll
;             for (int q = 0; q < 4; ++q) gw[i][q] = *(const u32x2*)(gp + i * 32 + q * 8);
; #pragma unroll
;         for (int i = 0; i < 4; ++i)
; #pragma unroll
;             for (int q = 0; q < 4; ++q) {
;                 float gv[4] = {bflo(gw[i][q].x), bfhi(gw[i][q].x), bflo(gw[i][q].y), bfhi(gw[i][q].y)}; float ov[4];
; #pragma unroll
;                 for (int e = 0; e < 4; ++e) { const float val = (o[i][q * 4 + e] * a0 + MB[(i * 16 + q * 4 + e) * 64] * a1) * inv; ov[e] = val * (gv[e] / (1.f + __expf(-gv[e]))); }
;                 *(u32x2*)(op + i * 32 + q * 8) = (u32x2){pk2(ov[0], ov[1]), pk2(ov[2], ov[3])};
;             }
.Le2_wd:
	s_xor_b32 s0, s21, 1
	s_mulk_i32 s0, 0x2200
	v_add_u32_e32 v150, s0, v104
	s_waitcnt lgkmcnt(0)
	s_barrier
	ds_read2st64_b32 v[70:71], v150 offset0:32 offset1:33
	ds_read2st64_b32 v[110:111], v150 offset0:0 offset1:1
	ds_read2st64_b32 v[112:113], v150 offset0:2 offset1:3
	ds_read2st64_b32 v[114:115], v150 offset0:4 offset1:5
	ds_read2st64_b32 v[116:117], v150 offset0:6 offset1:7
	ds_read2st64_b32 v[118:119], v150 offset0:8 offset1:9
	ds_read2st64_b32 v[120:121], v150 offset0:10 offset1:11
	ds_read2st64_b32 v[122:123], v150 offset0:12 offset1:13
	ds_read2st64_b32 v[124:125], v150 offset0:14 offset1:15
	ds_read2st64_b32 v[126:127], v150 offset0:16 offset1:17
	ds_read2st64_b32 v[128:129], v150 offset0:18 offset1:19
	ds_read2st64_b32 v[130:131], v150 offset0:20 offset1:21
	ds_read2st64_b32 v[132:133], v150 offset0:22 offset1:23
	ds_read2st64_b32 v[134:135], v150 offset0:24 offset1:25
	ds_read2st64_b32 v[136:137], v150 offset0:26 offset1:27
	ds_read2st64_b32 v[138:139], v150 offset0:28 offset1:29
	ds_read2st64_b32 v[140:141], v150 offset0:30 offset1:31
	v_max_f32_e32 v0, v204, v204
	s_lshl_b32 s92, s2, 8
	v_ashrrev_i32_e32 v183, 31, v182
	v_lshlrev_b64 v[102:103], 1, v[182:183]
	s_waitcnt lgkmcnt(0)
	v_max_f32_e32 v66, v70, v70
	v_max_f32_e32 v0, v0, v66
	v_sub_f32_e32 v66, v204, v0
	v_sub_f32_e32 v0, v70, v0
	v_exp_f32_e32 v66, v66
	v_exp_f32_e32 v67, v0
	v_mov_b32_e32 v69, v71
	v_lshlrev_b32_e32 v0, 12, v202
	s_mov_b64 s[0:1], 0x4600c00
	v_pk_mul_f32 v[68:69], v[68:69], v[66:67]
	s_nop 0
	v_add_f32_e32 v105, v68, v69
	v_lshl_add_u64 v[68:69], s[50:51], 0, v[0:1]
	v_lshl_add_u64 v[70:71], v[68:69], 0, s[92:93]
	v_lshlrev_b32_e32 v0, 11, v202
	v_lshl_add_u64 v[70:71], v[70:71], 0, v[102:103]
	v_sub_co_u32_e32 v72, vcc, 0, v0
	v_lshl_add_u64 v[106:107], v[70:71], 0, s[0:1]
	s_nop 0
	v_subb_co_u32_e64 v73, s[0:1], 0, 0, vcc
	s_mov_b32 s0, 0x4600000
	s_nop 0
	v_add_co_u32_e32 v70, vcc, s0, v70
	v_lshl_add_u64 v[68:69], v[68:69], 0, v[72:73]
	s_nop 0
	v_addc_co_u32_e32 v71, vcc, 0, v71, vcc
	s_lshl_b32 vcc_lo, s21, 7
	v_lshl_add_u32 v152, v182, 1, vcc_lo
	v_div_scale_f32 v0, s[0:1], v105, v105, 1.0
	v_rcp_f32_e32 v106, v0
	v_lshl_add_u64 v[68:69], v[68:69], 0, s[92:93]
	v_lshl_add_u64 v[102:103], v[68:69], 0, v[102:103]
	s_mov_b64 s[0:1], 0xae00400
	v_fma_f32 v107, -v0, v106, 1.0
	v_fmac_f32_e32 v106, v107, v106
	v_div_scale_f32 v107, vcc, 1.0, v105, 1.0
	v_mul_f32_e32 v108, v107, v106
	v_fma_f32 v109, -v0, v108, v107
	v_fmac_f32_e32 v108, v109, v106
	v_fma_f32 v0, -v0, v108, v107
	v_div_fmas_f32 v0, v0, v106, v108
	v_div_fixup_f32 v0, v0, v105, 1.0
	v_lshl_add_u64 v[68:69], v[102:103], 0, s[0:1]
	v_mov_b32_e32 v72, v67
	v_mov_b32_e32 v153, 0
	v_lshl_add_u64 v[148:149], v[152:153], 0, v[68:69]
	s_waitcnt vmcnt(6)
	v_pk_mul_f32 v[154:155], v[72:73], v[110:111] op_sel_hi:[0,1]
	v_pk_mul_f32 v[156:157], v[72:73], v[112:113] op_sel_hi:[0,1]
	v_pk_mul_f32 v[158:159], v[72:73], v[114:115] op_sel_hi:[0,1]
	v_pk_mul_f32 v[160:161], v[72:73], v[116:117] op_sel_hi:[0,1]
	v_lshlrev_b32_e32 v162, 16, v230
	v_and_b32_e32 v163, 0xffff0000, v230
	v_lshlrev_b32_e32 v164, 16, v231
	v_and_b32_e32 v165, 0xffff0000, v231
	v_lshlrev_b32_e32 v166, 16, v232
	v_and_b32_e32 v167, 0xffff0000, v232
	v_lshlrev_b32_e32 v168, 16, v233
	v_and_b32_e32 v169, 0xffff0000, v233
	v_pk_fma_f32 v[154:155], v[50:51], v[66:67], v[154:155] op_sel_hi:[1,0,1]
	v_pk_fma_f32 v[156:157], v[52:53], v[66:67], v[156:157] op_sel_hi:[1,0,1]
	v_pk_fma_f32 v[158:159], v[54:55], v[66:67], v[158:159] op_sel_hi:[1,0,1]
	v_pk_fma_f32 v[160:161], v[56:57], v[66:67], v[160:161] op_sel_hi:[1,0,1]
	v_mul_f32_e32 v170, 0xbfb8aa3b, v162
	v_mul_f32_e32 v171, 0xbfb8aa3b, v163
	v_mul_f32_e32 v172, 0xbfb8aa3b, v164
	v_mul_f32_e32 v173, 0xbfb8aa3b, v165
	v_mul_f32_e32 v174, 0xbfb8aa3b, v166
	v_mul_f32_e32 v175, 0xbfb8aa3b, v167
	v_mul_f32_e32 v176, 0xbfb8aa3b, v168
	v_mul_f32_e32 v177, 0xbfb8aa3b, v169
	v_pk_mul_f32 v[154:155], v[0:1], v[154:155] op_sel_hi:[0,1]
	v_pk_mul_f32 v[156:157], v[0:1], v[156:157] op_sel_hi:[0,1]
	v_pk_mul_f32 v[158:159], v[0:1], v[158:159] op_sel_hi:[0,1]
	v_pk_mul_f32 v[160:161], v[0:1], v[160:161] op_sel_hi:[0,1]
	v_exp_f32_e32 v170, v170
	v_exp_f32_e32 v171, v171
	v_exp_f32_e32 v172, v172
	v_exp_f32_e32 v173, v173
	v_exp_f32_e32 v174, v174
	v_exp_f32_e32 v175, v175
	v_exp_f32_e32 v176, v176
	v_exp_f32_e32 v177, v177
	v_pk_add_f32 v[170:171], v[170:171], 1.0 op_sel_hi:[1,0]
	v_pk_add_f32 v[172:173], v[172:173], 1.0 op_sel_hi:[1,0]
	v_pk_add_f32 v[174:175], v[174:175], 1.0 op_sel_hi:[1,0]
	v_pk_add_f32 v[176:177], v[176:177], 1.0 op_sel_hi:[1,0]
	v_rcp_f32_e32 v170, v170
	v_rcp_f32_e32 v171, v171
	v_rcp_f32_e32 v172, v172
	v_rcp_f32_e32 v173, v173
	v_rcp_f32_e32 v174, v174
	v_rcp_f32_e32 v175, v175
	v_rcp_f32_e32 v176, v176
	v_rcp_f32_e32 v177, v177
	v_pk_mul_f32 v[162:163], v[162:163], v[170:171]
	v_pk_mul_f32 v[164:165], v[164:165], v[172:173]
	v_pk_mul_f32 v[166:167], v[166:167], v[174:175]
	v_pk_mul_f32 v[168:169], v[168:169], v[176:177]
	v_pk_mul_f32 v[154:155], v[162:163], v[154:155]
	v_pk_mul_f32 v[156:157], v[164:165], v[156:157]
	v_pk_mul_f32 v[158:159], v[166:167], v[158:159]
	v_pk_mul_f32 v[160:161], v[168:169], v[160:161]
	v_cvt_pk_bf16_f32 v90, v154, v155
	v_cvt_pk_bf16_f32 v91, v156, v157
	v_cvt_pk_bf16_f32 v92, v158, v159
	v_cvt_pk_bf16_f32 v93, v160, v161
	v_mbcnt_lo_u32_b32 v178, -1, 0
	v_mbcnt_hi_u32_b32 v178, -1, v178
	s_mul_i32 s4, s33, 0x1200
	s_add_u32 s4, s4, 0x11000
	v_and_b32_e32 v179, 31, v178
	v_lshrrev_b32_e32 v180, 5, v178
	v_mul_u32_u24_e32 v179, 0x90, v179
	v_lshl_add_u32 v179, v180, 3, v179
	v_add_u32_e32 v179, s4, v179
	v_readfirstlane_b32 s0, v148
	v_readfirstlane_b32 s1, v149
	ds_write_b64 v179, v[90:91] offset:0
	ds_write_b64 v179, v[92:93] offset:16
	s_waitcnt vmcnt(4)
; DI unsigned pk2(float lo, float hi) { f32x2 v = {lo, hi}; return __builtin_bit_cast(unsigned, __builtin_convertvector(v, bf2_t)); }
; DI float bflo(unsigned w) { return __uint_as_float(w << 16); }
; DI float bfhi(unsigned w) { return __uint_as_float(w & 0xffff0000u); }
; DI void attn_unit(const Params& p, int b, int h, int qb, LAS unsigned char* lds, int tid, int lane, int wave) {
;     ...
; #pragma unroll
;         for (int i = 0; i < 4; ++i)
; #pragma unroll
;             for (int q = 0; q < 4; ++q) gw[i][q] = *(const u32x2*)(gp + i * 32 + q * 8);
; #pragma unroll
;         for (int i = 0; i < 4; ++i)
; #pragma unroll
;             for (int q = 0; q < 4; ++q) {
;                 float gv[4] = {bflo(gw[i][q].x), bfhi(gw[i][q].x), bflo(gw[i][q].y), bfhi(gw[i][q].y)}; float ov[4];
; #pragma unroll
;                 for (int e = 0; e < 4; ++e) { const float val = (o[i][q * 4 + e] * a0 + MB[(i * 16 + q * 4 + e) * 64] * a1) * inv; ov[e] = val * (gv[e] / (1.f + __expf(-gv[e]))); }
;                 *(u32x2*)(op + i * 32 + q * 8) = (u32x2){pk2(ov[0], ov[1]), pk2(ov[2], ov[3])};
;             }
	v_pk_mul_f32 v[154:155], v[72:73], v[118:119] op_sel_hi:[0,1]
	v_pk_mul_f32 v[156:157], v[72:73], v[120:121] op_sel_hi:[0,1]
	v_pk_mul_f32 v[158:159], v[72:73], v[122:123] op_sel_hi:[0,1]
	v_pk_mul_f32 v[160:161], v[72:73], v[124:125] op_sel_hi:[0,1]
	v_lshlrev_b32_e32 v162, 16, v234
	v_and_b32_e32 v163, 0xffff0000, v234
	v_lshlrev_b32_e32 v164, 16, v235
	v_and_b32_e32 v165, 0xffff0000, v235
	v_lshlrev_b32_e32 v166, 16, v236
	v_and_b32_e32 v167, 0xffff0000, v236
	v_lshlrev_b32_e32 v168, 16, v237
	v_and_b32_e32 v169, 0xffff0000, v237
	v_pk_fma_f32 v[154:155], v[58:59], v[66:67], v[154:155] op_sel_hi:[1,0,1]
	v_pk_fma_f32 v[156:157], v[60:61], v[66:67], v[156:157] op_sel_hi:[1,0,1]
	v_pk_fma_f32 v[158:159], v[62:63], v[66:67], v[158:159] op_sel_hi:[1,0,1]
	v_pk_fma_f32 v[160:161], v[64:65], v[66:67], v[160:161] op_sel_hi:[1,0,1]
	v_mul_f32_e32 v170, 0xbfb8aa3b, v162
	v_mul_f32_e32 v171, 0xbfb8aa3b, v163
	v_mul_f32_e32 v172, 0xbfb8aa3b, v164
	v_mul_f32_e32 v173, 0xbfb8aa3b, v165
	v_mul_f32_e32 v174, 0xbfb8aa3b, v166
	v_mul_f32_e32 v175, 0xbfb8aa3b, v167
	v_mul_f32_e32 v176, 0xbfb8aa3b, v168
	v_mul_f32_e32 v177, 0xbfb8aa3b, v169
	v_pk_mul_f32 v[154:155], v[0:1], v[154:155] op_sel_hi:[0,1]
	v_pk_mul_f32 v[156:157], v[0:1], v[156:157] op_sel_hi:[0,1]
	v_pk_mul_f32 v[158:159], v[0:1], v[158:159] op_sel_hi:[0,1]
	v_pk_mul_f32 v[160:161], v[0:1], v[160:161] op_sel_hi:[0,1]
	v_exp_f32_e32 v170, v170
	v_exp_f32_e32 v171, v171
	v_exp_f32_e32 v172, v172
	v_exp_f32_e32 v173, v173
	v_exp_f32_e32 v174, v174
	v_exp_f32_e32 v175, v175
	v_exp_f32_e32 v176, v176
	v_exp_f32_e32 v177, v177
	v_pk_add_f32 v[170:171], v[170:171], 1.0 op_sel_hi:[1,0]
	v_pk_add_f32 v[172:173], v[172:173], 1.0 op_sel_hi:[1,0]
	v_pk_add_f32 v[174:175], v[174:175], 1.0 op_sel_hi:[1,0]
	v_pk_add_f32 v[176:177], v[176:177], 1.0 op_sel_hi:[1,0]
	v_rcp_f32_e32 v170, v170
	v_rcp_f32_e32 v171, v171
	v_rcp_f32_e32 v172, v172
	v_rcp_f32_e32 v173, v173
	v_rcp_f32_e32 v174, v174
	v_rcp_f32_e32 v175, v175
	v_rcp_f32_e32 v176, v176
	v_rcp_f32_e32 v177, v177
	v_pk_mul_f32 v[162:163], v[162:163], v[170:171]
	v_pk_mul_f32 v[164:165], v[164:165], v[172:173]
	v_pk_mul_f32 v[166:167], v[166:167], v[174:175]
	v_pk_mul_f32 v[168:169], v[168:169], v[176:177]
	v_pk_mul_f32 v[154:155], v[162:163], v[154:155]
	v_pk_mul_f32 v[156:157], v[164:165], v[156:157]
	v_pk_mul_f32 v[158:159], v[166:167], v[158:159]
	v_pk_mul_f32 v[160:161], v[168:169], v[160:161]
	v_cvt_pk_bf16_f32 v94, v154, v155
	v_cvt_pk_bf16_f32 v95, v156, v157
	v_cvt_pk_bf16_f32 v96, v158, v159
	v_cvt_pk_bf16_f32 v97, v160, v161
	ds_write_b64 v179, v[94:95] offset:32
	ds_write_b64 v179, v[96:97] offset:48
	s_waitcnt vmcnt(2)
	v_pk_mul_f32 v[154:155], v[72:73], v[126:127] op_sel_hi:[0,1]
	v_pk_mul_f32 v[156:157], v[72:73], v[128:129] op_sel_hi:[0,1]
	v_pk_mul_f32 v[158:159], v[72:73], v[130:131] op_sel_hi:[0,1]
	v_pk_mul_f32 v[160:161], v[72:73], v[132:133] op_sel_hi:[0,1]
	v_lshlrev_b32_e32 v162, 16, v238
	v_and_b32_e32 v163, 0xffff0000, v238
	v_lshlrev_b32_e32 v164, 16, v239
	v_and_b32_e32 v165, 0xffff0000, v239
	v_lshlrev_b32_e32 v166, 16, v240
	v_and_b32_e32 v167, 0xffff0000, v240
	v_lshlrev_b32_e32 v168, 16, v241
	v_and_b32_e32 v169, 0xffff0000, v241
	v_pk_fma_f32 v[154:155], v[34:35], v[66:67], v[154:155] op_sel_hi:[1,0,1]
	v_pk_fma_f32 v[156:157], v[36:37], v[66:67], v[156:157] op_sel_hi:[1,0,1]
	v_pk_fma_f32 v[158:159], v[38:39], v[66:67], v[158:159] op_sel_hi:[1,0,1]
	v_pk_fma_f32 v[160:161], v[40:41], v[66:67], v[160:161] op_sel_hi:[1,0,1]
	v_mul_f32_e32 v170, 0xbfb8aa3b, v162
	v_mul_f32_e32 v171, 0xbfb8aa3b, v163
	v_mul_f32_e32 v172, 0xbfb8aa3b, v164
	v_mul_f32_e32 v173, 0xbfb8aa3b, v165
	v_mul_f32_e32 v174, 0xbfb8aa3b, v166
	v_mul_f32_e32 v175, 0xbfb8aa3b, v167
	v_mul_f32_e32 v176, 0xbfb8aa3b, v168
	v_mul_f32_e32 v177, 0xbfb8aa3b, v169
	v_pk_mul_f32 v[154:155], v[0:1], v[154:155] op_sel_hi:[0,1]
	v_pk_mul_f32 v[156:157], v[0:1], v[156:157] op_sel_hi:[0,1]
	v_pk_mul_f32 v[158:159], v[0:1], v[158:159] op_sel_hi:[0,1]
	v_pk_mul_f32 v[160:161], v[0:1], v[160:161] op_sel_hi:[0,1]
	v_exp_f32_e32 v170, v170
	v_exp_f32_e32 v171, v171
	v_exp_f32_e32 v172, v172
	v_exp_f32_e32 v173, v173
	v_exp_f32_e32 v174, v174
	v_exp_f32_e32 v175, v175
	v_exp_f32_e32 v176, v176
	v_exp_f32_e32 v177, v177
	v_pk_add_f32 v[170:171], v[170:171], 1.0 op_sel_hi:[1,0]
	v_pk_add_f32 v[172:173], v[172:173], 1.0 op_sel_hi:[1,0]
	v_pk_add_f32 v[174:175], v[174:175], 1.0 op_sel_hi:[1,0]
	v_pk_add_f32 v[176:177], v[176:177], 1.0 op_sel_hi:[1,0]
	v_rcp_f32_e32 v170, v170
	v_rcp_f32_e32 v171, v171
	v_rcp_f32_e32 v172, v172
	v_rcp_f32_e32 v173, v173
	v_rcp_f32_e32 v174, v174
	v_rcp_f32_e32 v175, v175
	v_rcp_f32_e32 v176, v176
	v_rcp_f32_e32 v177, v177
	v_pk_mul_f32 v[162:163], v[162:163], v[170:171]
	v_pk_mul_f32 v[164:165], v[164:165], v[172:173]
	v_pk_mul_f32 v[166:167], v[166:167], v[174:175]
	v_pk_mul_f32 v[168:169], v[168:169], v[176:177]
	v_pk_mul_f32 v[154:155], v[162:163], v[154:155]
	v_pk_mul_f32 v[156:157], v[164:165], v[156:157]
	v_pk_mul_f32 v[158:159], v[166:167], v[158:159]
	v_pk_mul_f32 v[160:161], v[168:169], v[160:161]
	v_cvt_pk_bf16_f32 v98, v154, v155
	v_cvt_pk_bf16_f32 v99, v156, v157
	v_cvt_pk_bf16_f32 v100, v158, v159
	v_cvt_pk_bf16_f32 v101, v160, v161
	ds_write_b64 v179, v[98:99] offset:64
	ds_write_b64 v179, v[100:101] offset:80
	s_waitcnt vmcnt(0)
; DI unsigned pk2(float lo, float hi) { f32x2 v = {lo, hi}; return __builtin_bit_cast(unsigned, __builtin_convertvector(v, bf2_t)); }
; DI float bflo(unsigned w) { return __uint_as_float(w << 16); }
; DI float bfhi(unsigned w) { return __uint_as_float(w & 0xffff0000u); }
; DI void attn_unit(const Params& p, int b, int h, int qb, LAS unsigned char* lds, int tid, int lane, int wave) {
;     ...
; #pragma unroll
;         for (int i = 0; i < 4; ++i)
; #pragma unroll
;             for (int q = 0; q < 4; ++q) gw[i][q] = *(const u32x2*)(gp + i * 32 + q * 8);
; #pragma unroll
;         for (int i = 0; i < 4; ++i)
; #pragma unroll
;             for (int q = 0; q < 4; ++q) {
;                 float gv[4] = {bflo(gw[i][q].x), bfhi(gw[i][q].x), bflo(gw[i][q].y), bfhi(gw[i][q].y)}; float ov[4];
; #pragma unroll
;                 for (int e = 0; e < 4; ++e) { const float val = (o[i][q * 4 + e] * a0 + MB[(i * 16 + q * 4 + e) * 64] * a1) * inv; ov[e] = val * (gv[e] / (1.f + __expf(-gv[e]))); }
;                 *(u32x2*)(op + i * 32 + q * 8) = (u32x2){pk2(ov[0], ov[1]), pk2(ov[2], ov[3])};
;             }
	v_pk_mul_f32 v[154:155], v[72:73], v[134:135] op_sel_hi:[0,1]
	v_pk_mul_f32 v[156:157], v[72:73], v[136:137] op_sel_hi:[0,1]
	v_pk_mul_f32 v[158:159], v[72:73], v[138:139] op_sel_hi:[0,1]
	v_pk_mul_f32 v[160:161], v[72:73], v[140:141] op_sel_hi:[0,1]
	v_lshlrev_b32_e32 v162, 16, v242
	v_and_b32_e32 v163, 0xffff0000, v242
	v_lshlrev_b32_e32 v164, 16, v243
	v_and_b32_e32 v165, 0xffff0000, v243
	v_lshlrev_b32_e32 v166, 16, v244
	v_and_b32_e32 v167, 0xffff0000, v244
	v_lshlrev_b32_e32 v168, 16, v245
	v_and_b32_e32 v169, 0xffff0000, v245
	v_pk_fma_f32 v[154:155], v[42:43], v[66:67], v[154:155] op_sel_hi:[1,0,1]
	v_pk_fma_f32 v[156:157], v[44:45], v[66:67], v[156:157] op_sel_hi:[1,0,1]
	v_pk_fma_f32 v[158:159], v[46:47], v[66:67], v[158:159] op_sel_hi:[1,0,1]
	v_pk_fma_f32 v[160:161], v[48:49], v[66:67], v[160:161] op_sel_hi:[1,0,1]
	v_mul_f32_e32 v170, 0xbfb8aa3b, v162
	v_mul_f32_e32 v171, 0xbfb8aa3b, v163
	v_mul_f32_e32 v172, 0xbfb8aa3b, v164
	v_mul_f32_e32 v173, 0xbfb8aa3b, v165
	v_mul_f32_e32 v174, 0xbfb8aa3b, v166
	v_mul_f32_e32 v175, 0xbfb8aa3b, v167
	v_mul_f32_e32 v176, 0xbfb8aa3b, v168
	v_mul_f32_e32 v177, 0xbfb8aa3b, v169
	v_pk_mul_f32 v[154:155], v[0:1], v[154:155] op_sel_hi:[0,1]
	v_pk_mul_f32 v[156:157], v[0:1], v[156:157] op_sel_hi:[0,1]
	v_pk_mul_f32 v[158:159], v[0:1], v[158:159] op_sel_hi:[0,1]
	v_pk_mul_f32 v[160:161], v[0:1], v[160:161] op_sel_hi:[0,1]
	v_exp_f32_e32 v170, v170
	v_exp_f32_e32 v171, v171
	v_exp_f32_e32 v172, v172
	v_exp_f32_e32 v173, v173
	v_exp_f32_e32 v174, v174
	v_exp_f32_e32 v175, v175
	v_exp_f32_e32 v176, v176
	v_exp_f32_e32 v177, v177
	v_pk_add_f32 v[170:171], v[170:171], 1.0 op_sel_hi:[1,0]
	v_pk_add_f32 v[172:173], v[172:173], 1.0 op_sel_hi:[1,0]
	v_pk_add_f32 v[174:175], v[174:175], 1.0 op_sel_hi:[1,0]
	v_pk_add_f32 v[176:177], v[176:177], 1.0 op_sel_hi:[1,0]
	v_rcp_f32_e32 v170, v170
	v_rcp_f32_e32 v171, v171
	v_rcp_f32_e32 v172, v172
	v_rcp_f32_e32 v173, v173
	v_rcp_f32_e32 v174, v174
	v_rcp_f32_e32 v175, v175
	v_rcp_f32_e32 v176, v176
	v_rcp_f32_e32 v177, v177
	v_pk_mul_f32 v[162:163], v[162:163], v[170:171]
	v_pk_mul_f32 v[164:165], v[164:165], v[172:173]
	v_pk_mul_f32 v[166:167], v[166:167], v[174:175]
	v_pk_mul_f32 v[168:169], v[168:169], v[176:177]
	v_pk_mul_f32 v[154:155], v[162:163], v[154:155]
	v_pk_mul_f32 v[156:157], v[164:165], v[156:157]
	v_pk_mul_f32 v[158:159], v[166:167], v[158:159]
	v_pk_mul_f32 v[160:161], v[168:169], v[160:161]
	v_cvt_pk_bf16_f32 v102, v154, v155
	v_cvt_pk_bf16_f32 v103, v156, v157
	v_cvt_pk_bf16_f32 v104, v158, v159
	v_cvt_pk_bf16_f32 v105, v160, v161
	ds_write_b64 v179, v[102:103] offset:96
	ds_write_b64 v179, v[104:105] offset:112
	v_lshrrev_b32_e32 v180, 3, v178
	v_and_b32_e32 v181, 7, v178
	v_mul_u32_u24_e32 v177, 0x90, v180
	v_lshl_add_u32 v177, v181, 4, v177
	v_add_u32_e32 v177, s4, v177
	v_lshlrev_b32_e32 v180, 11, v180
	v_lshl_add_u32 v180, v181, 4, v180
	s_waitcnt lgkmcnt(0)
	ds_read_b128 v[154:157], v177
	ds_read_b128 v[158:161], v177 offset:1152
	ds_read_b128 v[162:165], v177 offset:2304
	ds_read_b128 v[166:169], v177 offset:3456
	s_waitcnt lgkmcnt(3)
	global_store_dwordx4 v180, v[154:157], s[0:1]
	s_add_u32 s0, s0, 0x4000
	s_addc_u32 s1, s1, 0
	s_waitcnt lgkmcnt(2)
	global_store_dwordx4 v180, v[158:161], s[0:1]
	s_add_u32 s0, s0, 0x4000
	s_addc_u32 s1, s1, 0
	s_waitcnt lgkmcnt(1)
	global_store_dwordx4 v180, v[162:165], s[0:1]
	s_add_u32 s0, s0, 0x4000
	s_addc_u32 s1, s1, 0
	s_waitcnt lgkmcnt(0)
	global_store_dwordx4 v180, v[166:169], s[0:1]
	s_branch .LBB0_425
